# prologue: transpose-finish no longer drains the next item's loads (counted waits moved to the end of each load block)
# baseline (speedup 1.0000x reference)
.LBB0_81:
	s_mov_b32 s91, s84
	s_branch .Ltrg2_go
.LBB0_82:
	s_waitcnt vmcnt(0)
.Ltrg2_go:
	v_cvt_f32_u32_e32 v73, s93
	s_sub_i32 s36, 0, s93
	s_abs_i32 s5, s92
	v_pk_mul_f32 v[100:101], v[86:87], v[28:29] op_sel_hi:[0,1]
	v_rcp_iflag_f32_e32 v73, v73
	v_pk_mul_f32 v[108:109], v[86:87], v[30:31] op_sel_hi:[0,1]
	ds_write2_b32 v81, v100, v101 offset1:1
	ds_write2_b32 v81, v108, v109 offset0:2 offset1:3
	v_pk_mul_f32 v[100:101], v[88:89], v[32:33] op_sel_hi:[0,1]
	v_mul_f32_e32 v73, 0x4f7ffffe, v73
	v_cvt_u32_f32_e32 v73, v73
	ds_write2_b32 v83, v100, v101 offset1:1
	v_pk_mul_f32 v[100:101], v[88:89], v[34:35] op_sel_hi:[0,1]
	ds_write2_b32 v85, v100, v101 offset1:1
	v_readfirstlane_b32 s37, v73
	s_mul_i32 s36, s36, s37
	s_mul_hi_u32 s36, s37, s36
	s_add_i32 s37, s37, s36
	s_mul_hi_u32 s36, s5, s37
	s_mul_i32 s37, s36, s93
	s_sub_i32 s5, s5, s37
	v_pk_mul_f32 v[100:101], v[90:91], v[40:41] op_sel_hi:[0,1]
	s_ashr_i32 s4, s92, 31
	s_add_i32 s38, s36, 1
	s_sub_i32 s37, s5, s93
	ds_write2_b32 v87, v100, v101 offset1:1
	v_pk_mul_f32 v[100:101], v[90:91], v[42:43] op_sel_hi:[0,1]
	s_cmp_ge_u32 s5, s93
	ds_write2_b32 v89, v100, v101 offset1:1
	v_pk_mul_f32 v[100:101], v[92:93], v[44:45] op_sel_hi:[0,1]
	s_cselect_b32 s36, s38, s36
	ds_write2_b32 v91, v100, v101 offset1:1
	v_pk_mul_f32 v[100:101], v[92:93], v[46:47] op_sel_hi:[0,1]
	s_cselect_b32 s5, s37, s5
	s_add_i32 s37, s36, 1
	ds_write2_b32 v93, v100, v101 offset1:1
	v_pk_mul_f32 v[100:101], v[94:95], v[48:49] op_sel_hi:[0,1]
	s_cmp_ge_u32 s5, s93
	ds_write2_b32 v95, v100, v101 offset1:1
	v_pk_mul_f32 v[100:101], v[94:95], v[50:51] op_sel_hi:[0,1]
	s_cselect_b32 s5, s37, s36
	ds_write2_b32 v97, v100, v101 offset1:1
	v_pk_mul_f32 v[100:101], v[96:97], v[52:53] op_sel_hi:[0,1]
	s_xor_b32 s5, s5, s4
	ds_write2_b32 v99, v100, v101 offset1:1
	v_pk_mul_f32 v[100:101], v[96:97], v[54:55] op_sel_hi:[0,1]
	s_sub_i32 s5, s5, s4
	ds_write2_b32 v102, v100, v101 offset1:1
	v_pk_mul_f32 v[100:101], v[98:99], v[56:57] op_sel_hi:[0,1]
	s_lshl_b32 s4, s5, 6
	ds_write2_b32 v103, v100, v101 offset1:1
	v_pk_mul_f32 v[100:101], v[98:99], v[58:59] op_sel_hi:[0,1]
	s_mul_i32 s5, s5, s93
	ds_write2_b32 v104, v100, v101 offset1:1
	v_pk_mul_f32 v[100:101], v[80:81], v[60:61] op_sel_hi:[0,1]
	s_sub_i32 s5, s92, s5
	ds_write2_b32 v105, v100, v101 offset1:1
	v_pk_mul_f32 v[100:101], v[80:81], v[62:63] op_sel_hi:[0,1]
	s_lshl_b32 s38, s5, 5
	v_or_b32_e32 v73, s94, v67
	ds_write2_b32 v106, v100, v101 offset1:1
	s_waitcnt lgkmcnt(0)
	v_add_u32_e32 v73, s38, v73
	ds_read2_b32 v[104:105], v77 offset0:33 offset1:41
	ds_read2_b32 v[106:107], v77 offset1:8
	ds_read2_b32 v[108:109], v77 offset0:66 offset1:74
	ds_read2_b32 v[110:111], v77 offset0:99 offset1:107
	ds_read2_b32 v[112:113], v77 offset0:132 offset1:140
	ds_read2_b32 v[114:115], v77 offset0:165 offset1:173
	ds_read2_b32 v[116:117], v77 offset0:198 offset1:206
	ds_read2_b32 v[118:119], v77 offset0:231 offset1:239
	v_ashrrev_i32_e32 v83, 31, v73
	v_mul_lo_u32 v83, s68, v83
	v_mul_lo_u32 v85, s69, v73
	v_mad_u64_u32 v[120:121], s[36:37], s68, v73, 0
	s_ashr_i32 s5, s4, 31
	v_add3_u32 v121, v121, v83, v85
	v_lshl_add_u64 v[120:121], v[120:121], 1, s[70:71]
	s_lshl_b64 s[4:5], s[4:5], 1
	v_or_b32_e32 v83, s94, v69
	v_lshl_add_u64 v[120:121], v[120:121], 0, s[4:5]
	v_mov_b32_e32 v73, v65
	v_add_u32_e32 v83, s38, v83
	s_waitcnt lgkmcnt(6)
	v_cvt_pk_bf16_f32 v100, v106, v104
	s_waitcnt lgkmcnt(4)
	v_cvt_pk_bf16_f32 v101, v108, v110
	s_waitcnt lgkmcnt(2)
	v_cvt_pk_bf16_f32 v102, v112, v114
	s_waitcnt lgkmcnt(0)
	v_cvt_pk_bf16_f32 v103, v116, v118
	v_lshl_add_u64 v[120:121], v[120:121], 0, v[72:73]
	v_ashrrev_i32_e32 v85, 31, v83
	global_store_dwordx4 v[120:121], v[100:103], off
	v_mul_lo_u32 v85, s68, v85
	v_mul_lo_u32 v87, s69, v83
	v_cvt_pk_bf16_f32 v100, v107, v105
	v_mad_u64_u32 v[104:105], s[36:37], s68, v83, 0
	v_add3_u32 v105, v105, v85, v87
	v_lshl_add_u64 v[104:105], v[104:105], 1, s[70:71]
	v_or_b32_e32 v83, s94, v71
	v_lshl_add_u64 v[104:105], v[104:105], 0, s[4:5]
	v_add_u32_e32 v83, s38, v83
	v_cvt_pk_bf16_f32 v101, v109, v111
	v_cvt_pk_bf16_f32 v102, v113, v115
	v_cvt_pk_bf16_f32 v103, v117, v119
	v_lshl_add_u64 v[104:105], v[104:105], 0, v[72:73]
	ds_read2_b32 v[106:107], v77 offset0:16 offset1:24
	ds_read2_b32 v[108:109], v77 offset0:49 offset1:57
	ds_read2_b32 v[110:111], v77 offset0:82 offset1:90
	ds_read2_b32 v[112:113], v77 offset0:115 offset1:123
	ds_read2_b32 v[114:115], v77 offset0:148 offset1:156
	ds_read2_b32 v[116:117], v77 offset0:181 offset1:189
	ds_read2_b32 v[118:119], v77 offset0:214 offset1:222
	ds_read2_b32 v[120:121], v77 offset0:247 offset1:255
	v_ashrrev_i32_e32 v85, 31, v83
	global_store_dwordx4 v[104:105], v[100:103], off
	v_mul_lo_u32 v85, s68, v85
	v_mul_lo_u32 v87, s69, v83
	v_mad_u64_u32 v[104:105], s[36:37], s68, v83, 0
	v_add3_u32 v105, v105, v85, v87
	v_lshl_add_u64 v[104:105], v[104:105], 1, s[70:71]
	v_or_b32_e32 v83, s94, v75
	v_lshl_add_u64 v[104:105], v[104:105], 0, s[4:5]
	v_add_u32_e32 v83, s38, v83
	s_waitcnt lgkmcnt(6)
	v_cvt_pk_bf16_f32 v100, v106, v108
	s_waitcnt lgkmcnt(4)
	v_cvt_pk_bf16_f32 v101, v110, v112
	s_waitcnt lgkmcnt(2)
	v_cvt_pk_bf16_f32 v102, v114, v116
	s_waitcnt lgkmcnt(0)
	v_cvt_pk_bf16_f32 v103, v118, v120
	v_lshl_add_u64 v[104:105], v[104:105], 0, v[72:73]
	v_ashrrev_i32_e32 v85, 31, v83
	global_store_dwordx4 v[104:105], v[100:103], off
	v_mul_lo_u32 v85, s68, v85
	v_mul_lo_u32 v87, s69, v83
	v_mad_u64_u32 v[104:105], s[36:37], s68, v83, 0
	v_add3_u32 v105, v105, v85, v87
	v_lshl_add_u64 v[104:105], v[104:105], 1, s[70:71]
	v_lshl_add_u64 v[104:105], v[104:105], 0, s[4:5]
	v_cvt_pk_bf16_f32 v100, v107, v109
	v_cvt_pk_bf16_f32 v101, v111, v113
	v_cvt_pk_bf16_f32 v102, v115, v117
	v_cvt_pk_bf16_f32 v103, v119, v121
	v_lshl_add_u64 v[104:105], v[104:105], 0, v[72:73]
	global_store_dwordx4 v[104:105], v[100:103], off
	s_waitcnt lgkmcnt(0)

.Ltrg1_tail:
	s_waitcnt vmcnt(7)
	s_and_b64 vcc, exec, s[4:5]
	s_cbranch_vccnz .Ltrg1_go
	v_mul_f32_e32 v86, v80, v206
	v_mul_f32_e32 v88, v80, v207
	v_mul_f32_e32 v90, v80, v208
	v_mul_f32_e32 v92, v80, v209
	v_mul_f32_e32 v94, v80, v210
	v_mul_f32_e32 v96, v80, v211
	v_mul_f32_e32 v98, v80, v212
	v_mul_f32_e32 v80, v80, v213
	s_branch .Ltrg1_go

.Ltrg1_go:
	s_lshr_b32 s5, s88, 5
	v_cvt_f32_u32_e32 v73, s5
	s_sub_i32 s37, 0, s5
	s_abs_i32 s36, s87
	v_pk_mul_f32 v[100:101], v[68:69], v[0:1] op_sel_hi:[0,1]
	v_rcp_iflag_f32_e32 v73, v73
	v_pk_mul_f32 v[102:103], v[68:69], v[2:3] op_sel_hi:[0,1]
	ds_write2_b32 v81, v100, v101 offset1:1
	ds_write2_b32 v81, v102, v103 offset0:2 offset1:3
	v_pk_mul_f32 v[100:101], v[70:71], v[4:5] op_sel_hi:[0,1]
	v_mul_f32_e32 v73, 0x4f7ffffe, v73
	v_cvt_u32_f32_e32 v73, v73
	v_add_u32_e32 v83, 0x420, v81
	s_ashr_i32 s4, s87, 31
	ds_write2_b32 v83, v100, v101 offset1:1
	v_readfirstlane_b32 s38, v73
	s_mul_i32 s37, s37, s38
	s_mul_hi_u32 s37, s38, s37
	s_add_i32 s38, s38, s37
	s_mul_hi_u32 s37, s36, s38
	s_mul_i32 s38, s37, s5
	s_sub_i32 s36, s36, s38
	s_add_i32 s39, s37, 1
	s_sub_i32 s38, s36, s5
	v_pk_mul_f32 v[100:101], v[70:71], v[6:7] op_sel_hi:[0,1]
	v_add_u32_e32 v85, 0x428, v81
	s_cmp_ge_u32 s36, s5
	ds_write2_b32 v85, v100, v101 offset1:1
	v_pk_mul_f32 v[100:101], v[74:75], v[8:9] op_sel_hi:[0,1]
	v_add_u32_e32 v87, 0x840, v81
	s_cselect_b32 s37, s39, s37
	ds_write2_b32 v87, v100, v101 offset1:1
	v_pk_mul_f32 v[100:101], v[74:75], v[10:11] op_sel_hi:[0,1]
	v_add_u32_e32 v89, 0x848, v81
	s_cselect_b32 s36, s38, s36
	s_add_i32 s38, s37, 1
	ds_write2_b32 v89, v100, v101 offset1:1
	v_pk_mul_f32 v[100:101], v[76:77], v[12:13] op_sel_hi:[0,1]
	v_add_u32_e32 v91, 0xc60, v81
	s_cmp_ge_u32 s36, s5
	ds_write2_b32 v91, v100, v101 offset1:1
	v_pk_mul_f32 v[100:101], v[76:77], v[14:15] op_sel_hi:[0,1]
	v_add_u32_e32 v93, 0xc68, v81
	s_cselect_b32 s36, s38, s37
	ds_write2_b32 v93, v100, v101 offset1:1
	v_pk_mul_f32 v[100:101], v[78:79], v[16:17] op_sel_hi:[0,1]
	v_add_u32_e32 v95, 0x1080, v81
	s_xor_b32 s36, s36, s4
	ds_write2_b32 v95, v100, v101 offset1:1
	v_pk_mul_f32 v[100:101], v[78:79], v[18:19] op_sel_hi:[0,1]
	v_add_u32_e32 v97, 0x1088, v81
	s_sub_i32 s36, s36, s4
	ds_write2_b32 v97, v100, v101 offset1:1
	v_pk_mul_f32 v[100:101], v[82:83], v[20:21] op_sel_hi:[0,1]
	v_add_u32_e32 v99, 0x14a0, v81
	s_lshl_b32 s4, s36, 6
	ds_write2_b32 v99, v100, v101 offset1:1
	v_pk_mul_f32 v[100:101], v[82:83], v[22:23] op_sel_hi:[0,1]
	v_add_u32_e32 v102, 0x14a8, v81
	s_mul_i32 s36, s36, s5
	ds_write2_b32 v102, v100, v101 offset1:1
	v_pk_mul_f32 v[100:101], v[84:85], v[24:25] op_sel_hi:[0,1]
	v_add_u32_e32 v103, 0x18c0, v81
	s_sub_i32 s5, s87, s36
	ds_write2_b32 v103, v100, v101 offset1:1
	v_pk_mul_f32 v[100:101], v[84:85], v[26:27] op_sel_hi:[0,1]
	v_add_u32_e32 v104, 0x18c8, v81
	s_lshl_b32 s36, s5, 5
	ds_write2_b32 v104, v100, v101 offset1:1
	v_pk_mul_f32 v[100:101], v[66:67], v[36:37] op_sel_hi:[0,1]
	v_add_u32_e32 v105, 0x1ce0, v81
	s_add_i32 s38, s36, s90
	ds_write2_b32 v105, v100, v101 offset1:1
	v_pk_mul_f32 v[100:101], v[66:67], v[38:39] op_sel_hi:[0,1]
	v_add_u32_e32 v106, 0x1ce8, v81
	v_add_u32_e32 v73, s38, v67
	ds_write2_b32 v106, v100, v101 offset1:1
	s_waitcnt lgkmcnt(0)
	v_mad_u64_u32 v[122:123], s[36:37], v73, s89, 0
	ds_read2_b32 v[100:101], v77 offset0:33 offset1:41
	ds_read2_b32 v[112:113], v77 offset1:8
	ds_read2_b32 v[114:115], v77 offset0:66 offset1:74
	ds_read2_b32 v[116:117], v77 offset0:99 offset1:107
	ds_read2_b32 v[118:119], v77 offset0:132 offset1:140
	ds_read2_b32 v[120:121], v77 offset0:165 offset1:173
	v_ashrrev_i32_e32 v107, 31, v73
	v_mov_b32_e32 v108, v123
	ds_read2_b32 v[126:127], v77 offset0:198 offset1:206
	ds_read2_b32 v[128:129], v77 offset0:231 offset1:239
	v_mad_u64_u32 v[124:125], s[36:37], v107, s89, v[108:109]
	s_ashr_i32 s5, s4, 31
	v_mov_b32_e32 v123, v124
	v_lshl_add_u64 v[122:123], v[122:123], 1, s[66:67]
	s_lshl_b64 s[4:5], s[4:5], 1
	v_lshl_add_u64 v[122:123], v[122:123], 0, s[4:5]
	v_mov_b32_e32 v73, v65
	s_waitcnt lgkmcnt(6)
	v_cvt_pk_bf16_f32 v108, v112, v100
	s_waitcnt lgkmcnt(4)
	v_cvt_pk_bf16_f32 v109, v114, v116
	s_waitcnt lgkmcnt(2)
	v_cvt_pk_bf16_f32 v110, v118, v120
	s_waitcnt lgkmcnt(0)
	v_cvt_pk_bf16_f32 v111, v126, v128
	v_lshl_add_u64 v[122:123], v[122:123], 0, v[72:73]
	v_add_u32_e32 v100, s38, v69
	global_store_dwordx4 v[122:123], v[108:111], off
	v_ashrrev_i32_e32 v107, 31, v100
	s_cmpk_gt_i32 s91, 0x30ff
	v_cvt_pk_bf16_f32 v108, v113, v101
	v_mad_u64_u32 v[100:101], s[36:37], v100, s89, 0
	v_mov_b32_e32 v112, v101
	v_mad_u64_u32 v[112:113], s[36:37], v107, s89, v[112:113]
	v_mov_b32_e32 v101, v112
	v_lshl_add_u64 v[100:101], v[100:101], 1, s[66:67]
	v_lshl_add_u64 v[100:101], v[100:101], 0, s[4:5]
	v_cvt_pk_bf16_f32 v109, v115, v117
	v_cvt_pk_bf16_f32 v110, v119, v121
	v_cvt_pk_bf16_f32 v111, v127, v129
	v_lshl_add_u64 v[100:101], v[100:101], 0, v[72:73]
	v_add_u32_e32 v107, s38, v71
	global_store_dwordx4 v[100:101], v[108:111], off
	v_mad_u64_u32 v[122:123], s[36:37], v107, s89, 0
	ds_read2_b32 v[100:101], v77 offset0:16 offset1:24
	ds_read2_b32 v[112:113], v77 offset0:49 offset1:57
	ds_read2_b32 v[114:115], v77 offset0:82 offset1:90
	ds_read2_b32 v[116:117], v77 offset0:115 offset1:123
	ds_read2_b32 v[118:119], v77 offset0:148 offset1:156
	ds_read2_b32 v[120:121], v77 offset0:181 offset1:189
	v_ashrrev_i32_e32 v109, 31, v107
	v_mov_b32_e32 v108, v123
	ds_read2_b32 v[126:127], v77 offset0:214 offset1:222
	ds_read2_b32 v[128:129], v77 offset0:247 offset1:255
	v_mad_u64_u32 v[124:125], s[36:37], v109, s89, v[108:109]
	v_mov_b32_e32 v123, v124
	v_lshl_add_u64 v[122:123], v[122:123], 1, s[66:67]
	v_lshl_add_u64 v[122:123], v[122:123], 0, s[4:5]
	s_waitcnt lgkmcnt(6)
	v_cvt_pk_bf16_f32 v108, v100, v112
	s_waitcnt lgkmcnt(4)
	v_cvt_pk_bf16_f32 v109, v114, v116
	s_waitcnt lgkmcnt(2)
	v_cvt_pk_bf16_f32 v110, v118, v120
	s_waitcnt lgkmcnt(0)
	v_cvt_pk_bf16_f32 v111, v126, v128
	v_lshl_add_u64 v[122:123], v[122:123], 0, v[72:73]
	v_add_u32_e32 v100, s38, v75
	global_store_dwordx4 v[122:123], v[108:111], off
	v_ashrrev_i32_e32 v107, 31, v100
	s_mov_b64 s[72:73], 0
	v_cvt_pk_bf16_f32 v108, v101, v113
	v_mad_u64_u32 v[100:101], s[36:37], v100, s89, 0
	v_mov_b32_e32 v112, v101
	v_mad_u64_u32 v[112:113], s[36:37], v107, s89, v[112:113]
	v_mov_b32_e32 v101, v112
	v_lshl_add_u64 v[100:101], v[100:101], 1, s[66:67]
	v_lshl_add_u64 v[100:101], v[100:101], 0, s[4:5]
	v_cvt_pk_bf16_f32 v109, v115, v117
	v_cvt_pk_bf16_f32 v110, v119, v121
	v_cvt_pk_bf16_f32 v111, v127, v129
	v_lshl_add_u64 v[100:101], v[100:101], 0, v[72:73]
	global_store_dwordx4 v[100:101], v[108:111], off
	s_waitcnt lgkmcnt(0)
	s_cbranch_scc1 .LBB0_83
	s_add_i32 s84, s91, 0x1000
	s_cmpk_lt_i32 s91, 0x2900
	s_cselect_b64 s[72:73], -1, 0
	s_and_b64 s[4:5], s[72:73], exec
	s_cselect_b32 s87, s84, s95
	s_cmpk_lt_i32 s87, 0xc00
	s_cselect_b64 s[4:5], -1, 0
	s_and_b64 vcc, exec, s[4:5]
	s_cbranch_vccnz .LBB0_155
	s_cmpk_gt_u32 s87, 0xfff
	s_cbranch_scc0 .LBB0_156
	s_cmpk_gt_u32 s87, 0x1aff
	s_cbranch_scc0 .LBB0_157
	s_cmpk_gt_u32 s87, 0x207f
	s_cbranch_scc0 .LBB0_158
	s_cmpk_gt_u32 s87, 0x227f
	s_cbranch_scc0 .LBB0_159
	s_cmpk_gt_u32 s87, 0x247f
	s_cbranch_scc0 .LBB0_160
	s_cmpk_gt_u32 s87, 0x267f
	s_cbranch_scc0 .LBB0_161
	s_cmpk_gt_u32 s87, 0x287f
	s_cbranch_scc0 .LBB0_164
	s_cmpk_gt_u32 s87, 0x337f
	s_cbranch_scc0 .LBB0_165
	v_readlane_b32 s36, v254, 0
	v_readlane_b32 s42, v254, 6
	v_readlane_b32 s43, v254, 7
	s_add_i32 s82, s87, 0xffffcc80
	s_mov_b64 s[66:67], 0
	s_mov_b64 s[78:79], 0
	v_readlane_b32 s37, v254, 1
	v_readlane_b32 s38, v254, 2
	v_readlane_b32 s39, v254, 3
	v_readlane_b32 s40, v254, 4
	v_readlane_b32 s41, v254, 5
	s_mov_b64 s[74:75], s[42:43]
	s_branch .LBB0_166

.LBB0_210:
	v_or_b32_e32 v36, 56, v36
	v_mul_lo_u32 v73, s77, v36
	v_mad_u64_u32 v[38:39], s[36:37], s76, v36, 0
	v_add3_u32 v39, v39, v37, v73
	v_lshl_add_u64 v[36:37], v[38:39], 2, s[74:75]
	v_lshl_add_u64 v[36:37], s[80:81], 2, v[36:37]
	v_lshl_add_u64 v[36:37], v[36:37], 0, v[64:65]
	global_load_dwordx4 v[36:39], v[36:37], off nt
	s_waitcnt vmcnt(7)
	s_and_b64 vcc, exec, s[4:5]
	s_cbranch_vccnz .LBB0_81
	v_mul_f32_e32 v68, v66, v206
	v_mul_f32_e32 v70, v66, v207
	v_mul_f32_e32 v74, v66, v208
	v_mul_f32_e32 v76, v66, v209
	v_mul_f32_e32 v78, v66, v210
	v_mul_f32_e32 v82, v66, v211
	v_mul_f32_e32 v84, v66, v212
	v_mul_f32_e32 v66, v66, v213
	s_branch .LBB0_81
